# scan: producer waves prefetch next group's first 14 raw tiles before the small-matrix section
# speedup vs baseline: 1.0802x; 1.0065x over previous
.LBB0_302:
	s_mov_b32 s96, 32
	s_barrier
	s_cmp_lt_i32 s96, 0
	s_cbranch_scc1 .LBB0_301
	s_ashr_i32 s22, s95, 4
	s_and_b32 s24, s95, 1
	s_bfe_i32 s33, s95, 0x10000
	s_ashr_i32 s23, s22, 31
	s_cmp_eq_u32 s24, 0
	s_cselect_b64 s[56:57], -1, 0
	s_lshl_b32 s58, s95, 5
	s_and_b32 s33, s33, 0x600
	s_and_b32 s60, s58, 0x1c0
	s_or_b32 s33, s33, s60
	s_lshl_b32 s58, s33, 1
	s_mov_b32 s59, s25
	v_or_b32_e32 v148, s60, v140
	v_lshl_add_u64 v[152:153], v[142:143], 0, s[58:59]
	v_readlane_b32 s58, v244, 15
	v_lshlrev_b32_e32 v6, 1, v148
	v_mov_b32_e32 v7, v34
	v_readlane_b32 s59, v244, 16
	v_or_b32_e32 v2, 0x400, v148
	v_or_b32_e32 v4, 0x408, v148
	v_lshl_add_u64 v[154:155], s[58:59], 0, v[6:7]
	v_readlane_b32 s58, v244, 17
	v_readlane_b32 s59, v244, 18
	v_mov_b32_e32 v32, v34
	v_mov_b32_e32 v33, v34
	v_lshl_add_u64 v[156:157], s[58:59], 0, v[6:7]
	v_mov_b32_e32 v35, v34
	v_lshlrev_b32_e32 v181, 2, v2
	v_lshlrev_b32_e32 v182, 2, v4
	v_mov_b64_e32 v[2:3], v[32:33]
	v_mov_b64_e32 v[6:7], v[32:33]
	v_mov_b64_e32 v[10:11], v[32:33]
	v_mov_b64_e32 v[14:15], v[32:33]
	s_mov_b32 s97, 0
	s_lshl_b64 s[22:23], s[22:23], 11
	v_or_b32_e32 v150, 8, v148
	s_lshl_b32 s24, s24, 15
	s_mov_b32 s76, -4
	s_lshl_b32 s77, s60, 2
	v_mov_b32_e32 v183, v173
	v_mov_b32_e32 v184, v172
	v_mov_b64_e32 v[4:5], v[34:35]
	v_mov_b64_e32 v[8:9], v[34:35]
	v_mov_b64_e32 v[12:13], v[34:35]
	v_mov_b64_e32 v[16:17], v[34:35]
	s_and_saveexec_b64 s[98:99], s[38:39]
	s_cbranch_execz .Lspf_skip0
	v_lshl_add_u32 v6, s97, 6, v151
	v_sub_u32_e32 v7, 0x7ff, v6
	v_cndmask_b32_e64 v8, v7, v6, s[56:57]
	v_ashrrev_i32_e32 v9, 31, v8
	v_lshl_add_u64 v[6:7], s[22:23], 0, v[8:9]
	v_mov_b64_e32 v[10:11], s[30:31]
	v_mad_u64_u32 v[12:13], s[100:101], v6, s89, v[10:11]
	v_mad_i32_i24 v13, v7, s89, v13
	v_lshlrev_b32_e32 v14, 1, v148
	v_mov_b32_e32 v15, v34
	v_lshl_add_u64 v[12:13], v[12:13], 0, v[14:15]
	s_mov_b64 s[100:101], 0x1000
	v_lshl_add_u64 v[14:15], v[12:13], 0, s[100:101]
	s_mov_b64 s[100:101], 0x3000
	v_lshl_add_u64 v[16:17], v[12:13], 0, s[100:101]
	v_lshl_add_u64 v[6:7], v[6:7], 0, s[24:25]
	v_lshlrev_b64 v[6:7], 10, v[6:7]
	v_lshl_add_u64 v[10:11], v[154:155], 0, v[6:7]
	v_lshl_add_u64 v[6:7], v[156:157], 0, v[6:7]
	v_mov_b32_e32 v56, 0
	v_mov_b32_e32 v57, 0
	v_mov_b32_e32 v58, 0
	v_mov_b32_e32 v59, 0
	v_mov_b32_e32 v60, 0
	v_mov_b32_e32 v61, 0
	v_mov_b32_e32 v62, 0
	v_mov_b32_e32 v63, 0
	v_mov_b32_e32 v68, 0
	v_mov_b32_e32 v69, 0
	v_mov_b32_e32 v70, 0
	v_mov_b32_e32 v71, 0
	v_mov_b32_e32 v72, 0
	v_mov_b32_e32 v73, 0
	v_mov_b32_e32 v74, 0
	v_mov_b32_e32 v75, 0
	v_mov_b32_e32 v92, 0
	v_mov_b32_e32 v93, 0
	v_mov_b32_e32 v94, 0
	v_mov_b32_e32 v95, 0
	v_mov_b32_e32 v96, 0
	v_mov_b32_e32 v97, 0
	v_mov_b32_e32 v98, 0
	v_mov_b32_e32 v99, 0
	v_mov_b32_e32 v100, 0
	v_mov_b32_e32 v101, 0
	v_mov_b32_e32 v102, 0
	v_mov_b32_e32 v103, 0
	v_mov_b32_e32 v104, 0
	v_mov_b32_e32 v105, 0
	v_mov_b32_e32 v106, 0
	v_mov_b32_e32 v107, 0
	global_load_dwordx4 v[84:87], v[14:15], off offset:1024
	global_load_dwordx4 v[88:91], v[14:15], off offset:1040
	global_load_dwordx4 v[52:55], v[14:15], off
	global_load_dwordx4 v[64:67], v[14:15], off offset:2048
	global_load_dwordx4 v[76:79], v[10:11], off
	global_load_dwordx4 v[80:83], v[6:7], off
	v_cmp_lt_i32_e32 vcc, 0, v8
	s_and_saveexec_b64 s[100:101], vcc
	global_load_dwordx4 v[96:99], v[12:13], off offset:-2816
	global_load_dwordx4 v[104:107], v[12:13], off offset:-2800
	global_load_dwordx4 v[56:59], v[12:13], off offset:-3840
	global_load_dwordx4 v[68:71], v[12:13], off offset:-1792
	s_mov_b64 exec, s[100:101]
	v_cmp_gt_i32_e32 vcc, 0x7ff, v8
	s_and_saveexec_b64 s[100:101], vcc
	global_load_dwordx4 v[92:95], v[16:17], off offset:768
	global_load_dwordx4 v[100:103], v[16:17], off offset:784
	global_load_dwordx4 v[60:63], v[16:17], off offset:-256
	global_load_dwordx4 v[72:75], v[16:17], off offset:1792
	s_mov_b64 exec, s[100:101]
.Lspf_skip0:
	s_mov_b64 exec, s[98:99]
	s_branch .LBB0_305

.LBB0_305:
	s_and_saveexec_b64 s[58:59], s[38:39]
	s_xor_b64 s[82:83], exec, s[58:59]
	s_cbranch_execz .LBB0_364
	s_cmp_ge_i32 s97, s96
	s_cbranch_scc1 .LBB0_364
	s_setprio 2
	v_lshl_add_u32 v18, s97, 6, v151
	v_sub_u32_e32 v19, 0x7ff, v18
	v_cndmask_b32_e64 v22, v19, v18, s[56:57]
	v_ashrrev_i32_e32 v23, 31, v22
	v_lshl_add_u64 v[18:19], s[22:23], 0, v[22:23]
	v_mov_b64_e32 v[20:21], s[30:31]
	v_mad_u64_u32 v[44:45], s[58:59], v18, s89, v[20:21]
	v_mad_i32_i24 v45, v19, s89, v45
	s_mov_b64 s[58:59], 0x1400
	v_lshl_add_u64 v[20:21], v[44:45], 0, s[58:59]
	v_lshlrev_b32_e32 v42, 1, v148
	v_mov_b32_e32 v43, v34
	v_lshl_add_u64 v[24:25], v[20:21], 0, v[42:43]
	v_cmp_lt_i32_e64 s[58:59], 0, v22
	s_and_saveexec_b64 s[60:61], s[58:59]
	s_cbranch_execz .LBB0_309
	v_lshl_add_u64 v[24:25], v[44:45], 0, v[42:43]
.LBB0_309:
	s_or_b64 exec, exec, s[60:61]
	s_load_dwordx4 s[68:71], s[80:81], 0x48
	s_load_dwordx4 s[64:67], s[80:81], 0x80
	s_movk_i32 s33, 0x7ff
	v_cmp_gt_i32_e64 s[60:61], s33, v22
	s_and_saveexec_b64 s[84:85], s[60:61]
	s_cbranch_execz .LBB0_311
	v_mov_b32_e32 v43, v34
	v_lshl_add_u64 v[22:23], v[44:45], 0, v[42:43]
	v_add_co_u32_e32 v22, vcc, 0x3000, v22
	s_nop 1
	v_addc_co_u32_e32 v23, vcc, 0, v23, vcc
.LBB0_311:
	s_or_b64 exec, exec, s[84:85]
	v_lshlrev_b32_e32 v46, 1, v150
	v_mov_b32_e32 v47, v34
	v_lshl_add_u64 v[20:21], v[20:21], 0, v[46:47]
	s_and_saveexec_b64 s[84:85], s[58:59]
	s_cbranch_execz .LBB0_313
	v_mov_b32_e32 v43, v34
	v_lshl_add_u64 v[20:21], v[44:45], 0, v[42:43]
.LBB0_313:
	s_or_b64 exec, exec, s[84:85]
	s_and_saveexec_b64 s[84:85], s[60:61]
	s_cbranch_execz .LBB0_315
	v_mov_b32_e32 v47, v34
	v_lshl_add_u64 v[20:21], v[44:45], 0, v[46:47]
	v_add_co_u32_e32 v20, vcc, 0x3000, v20
	s_nop 1
	v_addc_co_u32_e32 v21, vcc, 0, v21, vcc
.LBB0_315:
	s_or_b64 exec, exec, s[84:85]
	s_mov_b64 s[84:85], 0x1000
	v_lshl_add_u64 v[20:21], v[44:45], 0, s[84:85]
	v_mov_b32_e32 v43, v34
	v_lshl_add_u64 v[22:23], v[20:21], 0, v[42:43]
	s_and_saveexec_b64 s[84:85], s[58:59]
	s_cbranch_execz .LBB0_317
	v_lshl_add_u64 v[22:23], v[44:45], 0, v[42:43]
.LBB0_317:
	s_or_b64 exec, exec, s[84:85]
	s_and_saveexec_b64 s[84:85], s[60:61]
	s_cbranch_execz .LBB0_319
	v_mov_b32_e32 v43, v34
	v_lshl_add_u64 v[22:23], v[44:45], 0, v[42:43]
	v_add_co_u32_e32 v22, vcc, 0x2000, v22
	s_nop 1
	v_addc_co_u32_e32 v23, vcc, 0, v23, vcc
.LBB0_319:
	s_or_b64 exec, exec, s[84:85]
	s_mov_b64 s[84:85], 0x1800
	v_lshl_add_u64 v[30:31], v[44:45], 0, s[84:85]
	v_mov_b32_e32 v43, v34
	v_lshl_add_u64 v[22:23], v[30:31], 0, v[42:43]
	s_and_saveexec_b64 s[84:85], s[58:59]
	s_cbranch_execz .LBB0_321
	v_lshl_add_u64 v[22:23], v[44:45], 0, v[42:43]
.LBB0_321:
	s_or_b64 exec, exec, s[84:85]
	s_and_saveexec_b64 s[84:85], s[60:61]
	s_cbranch_execz .LBB0_323
	v_mov_b32_e32 v43, v34
	v_lshl_add_u64 v[22:23], v[44:45], 0, v[42:43]
	v_add_co_u32_e32 v22, vcc, 0x3000, v22
	s_nop 1
	v_addc_co_u32_e32 v23, vcc, 0, v23, vcc
.LBB0_323:
	s_or_b64 exec, exec, s[84:85]
	v_lshl_add_u64 v[18:19], v[18:19], 0, s[24:25]
	v_lshlrev_b64 v[18:19], 10, v[18:19]
	v_mov_b32_e32 v47, v34
	v_lshl_add_u64 v[48:49], v[154:155], 0, v[18:19]
	v_lshl_add_u64 v[50:51], v[156:157], 0, v[18:19]
	v_lshl_add_u64 v[18:19], v[20:21], 0, v[46:47]
	v_mov_b32_e32 v26, 0
	global_load_dwordx4 v[18:21], v[18:19], off
	v_mov_b32_e32 v22, 0
	v_mov_b32_e32 v23, 0
	v_mov_b32_e32 v24, 0
	v_mov_b32_e32 v25, 0
	s_and_saveexec_b64 s[84:85], s[58:59]
	s_cbranch_execz .LBB0_325
	v_mov_b32_e32 v43, v34
	v_lshl_add_u64 v[22:23], v[44:45], 0, v[42:43]
	global_load_dwordx4 v[22:25], v[22:23], off offset:-3824

.LBB0_363:
	s_or_b64 exec, exec, s[58:59]
	v_sub_f32_e32 v39, v39, v33
	v_mul_f32_e32 v39, 0x3fb8aa3b, v39
	v_exp_f32_e32 v39, v39
	v_cvt_f32_f16_sdwa v43, v21 dst_sel:DWORD dst_unused:UNUSED_PAD src0_sel:WORD_1
	v_cvt_f32_f16_sdwa v75, v25 dst_sel:DWORD dst_unused:UNUSED_PAD src0_sel:WORD_1
	v_cvt_f32_f16_e32 v25, v25
	v_mul_f32_e32 v39, v51, v39
	v_cvt_f32_f16_e32 v51, v21
	v_cvt_f32_f16_sdwa v78, v29 dst_sel:DWORD dst_unused:UNUSED_PAD src0_sel:WORD_1
	v_cvt_f32_f16_e32 v29, v29
	v_sub_f32_e32 v75, v75, v43
	v_sub_f32_e32 v25, v25, v51
	v_fma_mix_f32 v67, v75, v67, v21 op_sel:[0,0,1] op_sel_hi:[0,0,1]
	v_fma_mix_f32 v21, v25, v66, v21 op_sel_hi:[0,0,1]
	v_sub_f32_e32 v25, v29, v51
	v_mul_f32_e32 v29, 0xbfb8aa3b, v69
	v_exp_f32_e32 v29, v29
	v_fmac_f32_e32 v21, v25, v62
	v_cvt_f32_f16_sdwa v62, v24 dst_sel:DWORD dst_unused:UNUSED_PAD src0_sel:WORD_1
	v_cvt_f32_f16_sdwa v66, v28 dst_sel:DWORD dst_unused:UNUSED_PAD src0_sel:WORD_1
	v_mul_f32_e32 v29, v21, v29
	v_cvt_f32_f16_sdwa v21, v20 dst_sel:DWORD dst_unused:UNUSED_PAD src0_sel:WORD_1
	v_cvt_f32_f16_e32 v24, v24
	v_cvt_f32_f16_e32 v28, v28
	v_sub_f32_e32 v25, v70, v69
	v_sub_f32_e32 v62, v62, v21
	v_fma_mix_f32 v62, v62, v65, v20 op_sel:[0,0,1] op_sel_hi:[0,0,1]
	v_sub_f32_e32 v21, v66, v21
	v_fmac_f32_e32 v62, v21, v61
	v_sub_f32_e32 v21, v38, v32
	v_mul_f32_e32 v21, 0x3fb8aa3b, v21
	v_exp_f32_e32 v21, v21
	v_mul_f32_e32 v38, 0xbfb8aa3b, v32
	v_mul_f32_e32 v32, 0x3fb8aa3b, v32
	v_exp_f32_e32 v32, v32
	v_mul_f32_e32 v21, v46, v21
	v_cvt_f32_f16_e32 v46, v20
	v_cvt_f32_f16_sdwa v61, v27 dst_sel:DWORD dst_unused:UNUSED_PAD src0_sel:WORD_1
	v_mul_f32_e32 v42, v32, v42
	v_mul_f32_e32 v32, v32, v50
	v_sub_f32_e32 v24, v24, v46
	v_fma_mix_f32 v20, v24, v64, v20 op_sel_hi:[0,0,1]
	v_sub_f32_e32 v24, v28, v46
	v_mul_f32_e32 v28, 0xbfb8aa3b, v68
	v_exp_f32_e32 v28, v28
	v_fmac_f32_e32 v20, v24, v60
	v_cvt_f32_f16_sdwa v50, v23 dst_sel:DWORD dst_unused:UNUSED_PAD src0_sel:WORD_1
	v_cvt_f32_f16_e32 v23, v23
	v_mul_f32_e32 v28, v20, v28
	v_cvt_f32_f16_sdwa v20, v19 dst_sel:DWORD dst_unused:UNUSED_PAD src0_sel:WORD_1
	v_cvt_f32_f16_e32 v27, v27
	v_sub_f32_e32 v24, v72, v68
	v_sub_f32_e32 v43, v78, v43
	v_sub_f32_e32 v50, v50, v20
	v_fma_mix_f32 v50, v50, v59, v19 op_sel:[0,0,1] op_sel_hi:[0,0,1]
	v_sub_f32_e32 v20, v61, v20
	v_fmac_f32_e32 v50, v20, v55
	v_sub_f32_e32 v20, v37, v31
	v_mul_f32_e32 v20, 0x3fb8aa3b, v20
	v_exp_f32_e32 v20, v20
	v_mul_f32_e32 v37, 0xbfb8aa3b, v31
	v_mul_f32_e32 v31, 0x3fb8aa3b, v31
	v_exp_f32_e32 v31, v31
	v_mul_f32_e32 v20, v45, v20
	v_cvt_f32_f16_e32 v45, v19
	v_mul_f32_e32 v25, 0x3fb8aa3b, v25
	v_mul_f32_e32 v41, v31, v41
	v_mul_f32_e32 v31, v31, v49
	v_sub_f32_e32 v23, v23, v45
	v_fma_mix_f32 v19, v23, v58, v19 op_sel_hi:[0,0,1]
	v_sub_f32_e32 v23, v27, v45
	v_mul_f32_e32 v27, 0xbfb8aa3b, v85
	v_exp_f32_e32 v27, v27
	v_fmac_f32_e32 v19, v23, v54
	v_cvt_f32_f16_sdwa v49, v22 dst_sel:DWORD dst_unused:UNUSED_PAD src0_sel:WORD_1
	v_cvt_f32_f16_sdwa v54, v26 dst_sel:DWORD dst_unused:UNUSED_PAD src0_sel:WORD_1
	v_mul_f32_e32 v27, v19, v27
	v_cvt_f32_f16_sdwa v19, v18 dst_sel:DWORD dst_unused:UNUSED_PAD src0_sel:WORD_1
	v_cvt_f32_f16_e32 v22, v22
	v_cvt_f32_f16_e32 v26, v26
	v_sub_f32_e32 v23, v86, v85
	v_sub_f32_e32 v49, v49, v19
	v_fma_mix_f32 v49, v49, v57, v18 op_sel:[0,0,1] op_sel_hi:[0,0,1]
	v_sub_f32_e32 v19, v54, v19
	v_fmac_f32_e32 v49, v19, v53
	v_sub_f32_e32 v19, v36, v30
	v_mul_f32_e32 v19, 0x3fb8aa3b, v19
	v_exp_f32_e32 v19, v19
	v_mul_f32_e32 v36, 0xbfb8aa3b, v30
	v_mul_f32_e32 v30, 0x3fb8aa3b, v30
	v_exp_f32_e32 v30, v30
	v_mul_f32_e32 v19, v44, v19
	v_cvt_f32_f16_e32 v44, v18
	v_mul_f32_e32 v24, 0x3fb8aa3b, v24
	v_mul_f32_e32 v23, 0x3fb8aa3b, v23
	v_fmac_f32_e32 v67, v43, v63
	v_sub_f32_e32 v22, v22, v44
	v_fma_mix_f32 v18, v22, v56, v18 op_sel_hi:[0,0,1]
	v_sub_f32_e32 v22, v26, v44
	v_sub_f32_e32 v44, v88, v92
	v_mul_f32_e32 v44, 0x3fb8aa3b, v44
	v_mul_f32_e32 v43, 0xbfb8aa3b, v33
	v_exp_f32_e32 v25, v25
	v_exp_f32_e32 v24, v24
	v_exp_f32_e32 v23, v23
	v_mul_f32_e32 v40, v30, v40
	v_mul_f32_e32 v30, v30, v48
	v_exp_f32_e32 v44, v44
	v_mul_f32_e32 v48, 0xbfb8aa3b, v92
	v_exp_f32_e32 v43, v43
	v_mul_f32_e32 v33, 0x3fb8aa3b, v33
	v_mul_f32_e32 v51, 0x3fb8aa3b, v69
	v_exp_f32_e32 v38, v38
	v_mul_f32_e32 v46, 0x3fb8aa3b, v68
	v_exp_f32_e32 v37, v37
	v_mul_f32_e32 v45, 0x3fb8aa3b, v85
	v_exp_f32_e32 v36, v36
	v_mul_f32_e32 v26, 0x3fb8aa3b, v92
	v_exp_f32_e32 v48, v48
	v_exp_f32_e32 v33, v33
	v_exp_f32_e32 v51, v51
	v_exp_f32_e32 v46, v46
	v_exp_f32_e32 v45, v45
	v_exp_f32_e32 v26, v26
	v_mul_f32_e32 v25, v74, v25
	v_mul_f32_e32 v24, v80, v24
	v_mul_f32_e32 v23, v90, v23
	v_fmac_f32_e32 v18, v22, v52
	v_mul_f32_e32 v22, v96, v44
	v_mul_f32_e32 v43, v67, v43
	v_mul_f32_e32 v38, v62, v38
	v_mul_f32_e32 v37, v50, v37
	v_mul_f32_e32 v36, v49, v36
	v_mul_f32_e32 v44, v18, v48
	v_cvt_pk_bf16_f32 v18, v22, v19
	v_cvt_pk_bf16_f32 v19, v23, v20
	v_cvt_pk_bf16_f32 v20, v24, v21
	v_cvt_pk_bf16_f32 v21, v25, v39
	v_mul_f32_e32 v47, v33, v47
	v_mul_f32_e32 v63, v51, v73
	v_mul_f32_e32 v60, v46, v76
	v_mul_f32_e32 v50, v45, v89
	v_mul_f32_e32 v48, v26, v84
	ds_write_b128 v102, v[18:21] offset:16
	v_cvt_pk_bf16_f32 v18, v44, v36
	v_cvt_pk_bf16_f32 v19, v27, v37
	v_cvt_pk_bf16_f32 v20, v28, v38
	v_cvt_pk_bf16_f32 v21, v29, v43
	v_mul_f32_e32 v33, v33, v71
	v_mul_f32_e32 v51, v51, v77
	v_mul_f32_e32 v46, v46, v87
	v_mul_f32_e32 v45, v45, v93
	v_mul_f32_e32 v26, v26, v103
	ds_write_b128 v102, v[18:21] offset:2320
	v_cvt_pk_bf16_f32 v18, v48, v40
	v_cvt_pk_bf16_f32 v19, v50, v41
	v_cvt_pk_bf16_f32 v20, v60, v42
	v_cvt_pk_bf16_f32 v21, v63, v47
	ds_write_b128 v162, v[18:21] offset:16
	v_cvt_pk_bf16_f32 v18, v26, v30
	v_cvt_pk_bf16_f32 v19, v45, v31
	v_cvt_pk_bf16_f32 v20, v46, v32
	v_cvt_pk_bf16_f32 v21, v51, v33
	ds_write_b128 v162, v[18:21] offset:2320
	s_add_i32 s98, s97, 1
	s_cmp_ge_i32 s98, s96
	s_cbranch_scc1 .Lspf_skip1
	v_lshl_add_u32 v6, s98, 6, v151
	v_sub_u32_e32 v7, 0x7ff, v6
	v_cndmask_b32_e64 v8, v7, v6, s[56:57]
	v_ashrrev_i32_e32 v9, 31, v8
	v_lshl_add_u64 v[6:7], s[22:23], 0, v[8:9]
	v_mov_b64_e32 v[10:11], s[30:31]
	v_mad_u64_u32 v[12:13], s[100:101], v6, s89, v[10:11]
	v_mad_i32_i24 v13, v7, s89, v13
	v_lshlrev_b32_e32 v14, 1, v148
	v_mov_b32_e32 v15, v34
	v_lshl_add_u64 v[12:13], v[12:13], 0, v[14:15]
	s_mov_b64 s[100:101], 0x1000
	v_lshl_add_u64 v[14:15], v[12:13], 0, s[100:101]
	s_mov_b64 s[100:101], 0x3000
	v_lshl_add_u64 v[16:17], v[12:13], 0, s[100:101]
	v_lshl_add_u64 v[6:7], v[6:7], 0, s[24:25]
	v_lshlrev_b64 v[6:7], 10, v[6:7]
	v_lshl_add_u64 v[10:11], v[154:155], 0, v[6:7]
	v_lshl_add_u64 v[6:7], v[156:157], 0, v[6:7]
	v_mov_b32_e32 v56, 0
	v_mov_b32_e32 v57, 0
	v_mov_b32_e32 v58, 0
	v_mov_b32_e32 v59, 0
	v_mov_b32_e32 v60, 0
	v_mov_b32_e32 v61, 0
	v_mov_b32_e32 v62, 0
	v_mov_b32_e32 v63, 0
	v_mov_b32_e32 v68, 0
	v_mov_b32_e32 v69, 0
	v_mov_b32_e32 v70, 0
	v_mov_b32_e32 v71, 0
	v_mov_b32_e32 v72, 0
	v_mov_b32_e32 v73, 0
	v_mov_b32_e32 v74, 0
	v_mov_b32_e32 v75, 0
	v_mov_b32_e32 v92, 0
	v_mov_b32_e32 v93, 0
	v_mov_b32_e32 v94, 0
	v_mov_b32_e32 v95, 0
	v_mov_b32_e32 v96, 0
	v_mov_b32_e32 v97, 0
	v_mov_b32_e32 v98, 0
	v_mov_b32_e32 v99, 0
	v_mov_b32_e32 v100, 0
	v_mov_b32_e32 v101, 0
	v_mov_b32_e32 v102, 0
	v_mov_b32_e32 v103, 0
	v_mov_b32_e32 v104, 0
	v_mov_b32_e32 v105, 0
	v_mov_b32_e32 v106, 0
	v_mov_b32_e32 v107, 0
	global_load_dwordx4 v[84:87], v[14:15], off offset:1024
	global_load_dwordx4 v[88:91], v[14:15], off offset:1040
	global_load_dwordx4 v[52:55], v[14:15], off
	global_load_dwordx4 v[64:67], v[14:15], off offset:2048
	global_load_dwordx4 v[76:79], v[10:11], off
	global_load_dwordx4 v[80:83], v[6:7], off
	v_cmp_lt_i32_e32 vcc, 0, v8
	s_and_saveexec_b64 s[100:101], vcc
	global_load_dwordx4 v[96:99], v[12:13], off offset:-2816
	global_load_dwordx4 v[104:107], v[12:13], off offset:-2800
	global_load_dwordx4 v[56:59], v[12:13], off offset:-3840
	global_load_dwordx4 v[68:71], v[12:13], off offset:-1792
	s_mov_b64 exec, s[100:101]
	v_cmp_gt_i32_e32 vcc, 0x7ff, v8
	s_and_saveexec_b64 s[100:101], vcc
	global_load_dwordx4 v[92:95], v[16:17], off offset:768
	global_load_dwordx4 v[100:103], v[16:17], off offset:784
	global_load_dwordx4 v[60:63], v[16:17], off offset:-256
	global_load_dwordx4 v[72:75], v[16:17], off offset:1792
	s_mov_b64 exec, s[100:101]
.Lspf_skip1:
	v_lshl_add_u32 v2, v163, 1, v35
	ds_read_b128 v[18:21], v170
	ds_read_b128 v[22:25], v170 offset:2304
	ds_read_b128 v[26:29], v2
	ds_read_b128 v[30:33], v2 offset:2304
	s_or_b64 vcc, s[54:55], s[42:43]
	s_waitcnt lgkmcnt(1)
	v_mfma_f32_16x16x32_bf16 v[36:39], v[18:21], v[26:29], 0
	v_mfma_f32_16x16x32_bf16 v[40:43], v[26:29], v[18:21], 0
	v_mfma_f32_16x16x32_bf16 v[26:29], v[22:25], v[26:29], 0
	s_waitcnt lgkmcnt(0)
	v_mfma_f32_16x16x32_bf16 v[18:21], v[18:21], v[30:33], 0
	v_mfma_f32_16x16x32_bf16 v[22:25], v[22:25], v[30:33], 0
	ds_read_b128 v[30:33], v170 offset:64
	ds_read_b128 v[44:47], v170 offset:2368
	ds_read_b128 v[48:51], v2 offset:64
	ds_read_b128 v[2:5], v2 offset:2368
	s_waitcnt lgkmcnt(0)
	v_mfma_f32_16x16x32_bf16 v[18:21], v[30:33], v[2:5], v[18:21]
	v_mfma_f32_16x16x32_bf16 v[26:29], v[44:47], v[48:51], v[26:29]
	s_nop 6
	v_cndmask_b32_e64 v20, v20, 0, s[46:47]
	v_cndmask_b32_e64 v21, v21, 0, s[50:51]
	v_mfma_f32_16x16x32_bf16 v[22:25], v[44:47], v[2:5], v[22:25]
	v_mfma_f32_16x16x32_bf16 v[36:39], v[30:33], v[48:51], v[36:39]
	v_cndmask_b32_e32 v26, 0, v26, vcc
	v_cndmask_b32_e64 v28, 0, v28, s[52:53]
	s_nop 4
	v_cndmask_b32_e64 v23, 0, v23, s[42:43]
	v_mfma_f32_16x16x32_bf16 v[40:43], v[48:51], v[30:33], v[40:43]
	v_mov_b32_e32 v30, s25
	v_cndmask_b32_e64 v31, v18, v30, s[44:45]
	v_mov_b32_e32 v32, s25
	v_cndmask_b32_e64 v31, v31, v18, s[42:43]
	v_cndmask_b32_e64 v18, 0, v27, s[54:55]
	v_cndmask_b32_e64 v32, v22, v32, s[44:45]
	v_cndmask_b32_e64 v33, 0, v19, s[42:43]
	v_cndmask_b32_e64 v19, 0, v29, s[48:49]
	v_cvt_pk_bf16_f32 v18, v26, v18
	v_lshlrev_b32_e32 v26, 1, v164
	v_cndmask_b32_e64 v30, v30, v40, s[44:45]
	v_cndmask_b32_e64 v22, v32, v22, s[42:43]
	v_cndmask_b32_e64 v40, v41, 0, s[42:43]
	v_cndmask_b32_e64 v24, v24, 0, s[46:47]
	v_cndmask_b32_e64 v41, 0, v42, s[46:47]
	v_cndmask_b32_e64 v25, v25, 0, s[50:51]
	v_cvt_pk_bf16_f32 v19, v28, v19
	v_add3_u32 v42, v35, v180, v26
	ds_write_b64 v42, v[18:19] offset:13056
	v_cvt_pk_bf16_f32 v18, v31, v33
	v_cvt_pk_bf16_f32 v19, v20, v21
	v_cvt_pk_bf16_f32 v20, v22, v23
	v_cvt_pk_bf16_f32 v21, v24, v25
	v_add3_u32 v22, v35, v165, v140
	ds_write_b128 v22, v[18:21] offset:14592
	v_cndmask_b32_e64 v19, 0, v39, s[48:49]
	v_cndmask_b32_e64 v20, 0, v38, s[52:53]
	v_cndmask_b32_e64 v18, 0, v37, s[54:55]
	v_cndmask_b32_e32 v21, 0, v36, vcc
	v_cndmask_b32_e64 v31, 0, v43, s[50:51]
	v_cvt_pk_bf16_f32 v32, v30, v40
	v_cvt_pk_bf16_f32 v33, v41, v31
	v_mov_b32_e32 v35, v34
	v_cvt_pk_bf16_f32 v18, v21, v18
	v_cvt_pk_bf16_f32 v19, v20, v19
	v_mov_b32_e32 v20, v34
	v_mov_b32_e32 v21, v34
	s_nop 1
	v_mfma_f32_16x16x32_bf16 v[22:25], v[32:35], v[18:21], 0
	v_mfma_f32_16x16x32_bf16 v[18:21], v[18:21], v[32:35], 0
	s_nop 6
	v_cvt_pk_bf16_f32 v22, v22, v23
	v_cvt_pk_bf16_f32 v32, v18, v19
	v_cvt_pk_bf16_f32 v33, v20, v21
	v_cvt_pk_bf16_f32 v23, v24, v25
	v_mov_b32_e32 v24, v34
	v_mov_b32_e32 v25, v34
	v_pk_add_f32 v[20:21], v[146:147], v[20:21]
	v_pk_add_f32 v[18:19], v[144:145], v[18:19]
	v_mfma_f32_16x16x32_bf16 v[26:29], v[32:35], v[22:25], 0
	v_mfma_f32_16x16x32_bf16 v[22:25], v[22:25], v[32:35], 0
	s_nop 6
	v_cvt_pk_bf16_f32 v26, v26, v27
	v_cvt_pk_bf16_f32 v32, v22, v23
	v_cvt_pk_bf16_f32 v33, v24, v25
	v_cvt_pk_bf16_f32 v27, v28, v29
	v_mov_b32_e32 v28, v34
	v_mov_b32_e32 v29, v34
	v_pk_add_f32 v[24:25], v[146:147], v[24:25]
	v_pk_add_f32 v[22:23], v[144:145], v[22:23]
	v_mfma_f32_16x16x32_bf16 v[26:29], v[32:35], v[26:29], 0
	v_cvt_pk_bf16_f32 v32, v22, v23
	v_cvt_pk_bf16_f32 v33, v24, v25
	v_mov_b32_e32 v24, v34
	v_mov_b32_e32 v25, v34
	s_nop 3
	v_pk_add_f32 v[28:29], v[146:147], v[28:29]
	v_pk_add_f32 v[26:27], v[144:145], v[26:27]
	v_cvt_pk_bf16_f32 v23, v28, v29
	v_cvt_pk_bf16_f32 v22, v26, v27
	s_nop 1
	v_mfma_f32_16x16x32_bf16 v[22:25], v[32:35], v[22:25], 0
	v_cvt_pk_bf16_f32 v32, v18, v19
	v_cvt_pk_bf16_f32 v33, v20, v21
	v_mov_b32_e32 v20, v34
	v_mov_b32_e32 v21, v34
	s_nop 3
	v_cvt_pk_bf16_f32 v18, v22, v23
	v_cvt_pk_bf16_f32 v19, v24, v25
	v_sub_f32_e32 v22, v147, v31
	v_sub_f32_e32 v23, v146, v41
	v_sub_f32_e32 v24, v144, v30
	v_sub_f32_e32 v25, v145, v40
	v_mfma_f32_16x16x32_bf16 v[18:21], v[32:35], v[18:21], 0
	v_cvt_pk_bf16_f32 v32, v24, v25
	v_cvt_pk_bf16_f32 v33, v23, v22
	s_nop 5
	v_cvt_pk_bf16_f32 v18, v18, v19
	v_cvt_pk_bf16_f32 v19, v20, v21
	v_mov_b32_e32 v20, v34
	v_mov_b32_e32 v21, v34
	s_nop 1
	v_mfma_f32_16x16x32_bf16 v[18:21], v[32:35], v[18:21], 0
	s_nop 7
	v_xor_b32_e32 v21, 0x80000000, v21
	v_xor_b32_e32 v20, 0x80000000, v20
	v_xor_b32_e32 v19, 0x80000000, v19
	v_xor_b32_e32 v18, 0x80000000, v18
	v_cvt_pk_bf16_f32 v18, v18, v19
	v_cvt_pk_bf16_f32 v19, v20, v21
	ds_write_b64 v42, v[18:19] offset:13824

	.amdhsa_kernel _Z4mega6Params
		.amdhsa_group_segment_fixed_size 0
		.amdhsa_private_segment_fixed_size 0
		.amdhsa_kernarg_size 520
		.amdhsa_user_sgpr_count 2
		.amdhsa_user_sgpr_dispatch_ptr 0
		.amdhsa_user_sgpr_queue_ptr 0
		.amdhsa_user_sgpr_kernarg_segment_ptr 1
		.amdhsa_user_sgpr_dispatch_id 0
		.amdhsa_user_sgpr_kernarg_preload_length 0
		.amdhsa_user_sgpr_kernarg_preload_offset 0
		.amdhsa_user_sgpr_private_segment_size 0
		.amdhsa_uses_dynamic_stack 0
		.amdhsa_enable_private_segment 0
		.amdhsa_system_sgpr_workgroup_id_x 1
		.amdhsa_system_sgpr_workgroup_id_y 0
		.amdhsa_system_sgpr_workgroup_id_z 0
		.amdhsa_system_sgpr_workgroup_info 0
		.amdhsa_system_vgpr_workitem_id 2
		.amdhsa_next_free_vgpr 256
		.amdhsa_next_free_sgpr 102
		.amdhsa_accum_offset 256
		.amdhsa_reserve_vcc 1
		.amdhsa_float_round_mode_32 0
		.amdhsa_float_round_mode_16_64 0
		.amdhsa_float_denorm_mode_32 3
		.amdhsa_float_denorm_mode_16_64 3
		.amdhsa_dx10_clamp 1
		.amdhsa_ieee_mode 1
		.amdhsa_fp16_overflow 0
		.amdhsa_tg_split 0
		.amdhsa_exception_fp_ieee_invalid_op 0
		.amdhsa_exception_fp_denorm_src 0
		.amdhsa_exception_fp_ieee_div_zero 0
		.amdhsa_exception_fp_ieee_overflow 0
		.amdhsa_exception_fp_ieee_underflow 0
		.amdhsa_exception_fp_ieee_inexact 0
		.amdhsa_exception_int_div_zero 0
	.end_amdhsa_kernel

amdhsa.kernels:
  - .agpr_count:     0
    .args:
      - .offset:         0
        .size:           264
        .value_kind:     by_value
      - .offset:         264
        .size:           4
        .value_kind:     hidden_block_count_x
      - .offset:         268
        .size:           4
        .value_kind:     hidden_block_count_y
      - .offset:         272
        .size:           4
        .value_kind:     hidden_block_count_z
      - .offset:         276
        .size:           2
        .value_kind:     hidden_group_size_x
      - .offset:         278
        .size:           2
        .value_kind:     hidden_group_size_y
      - .offset:         280
        .size:           2
        .value_kind:     hidden_group_size_z
      - .offset:         282
        .size:           2
        .value_kind:     hidden_remainder_x
      - .offset:         284
        .size:           2
        .value_kind:     hidden_remainder_y
      - .offset:         286
        .size:           2
        .value_kind:     hidden_remainder_z
      - .offset:         304
        .size:           8
        .value_kind:     hidden_global_offset_x
      - .offset:         312
        .size:           8
        .value_kind:     hidden_global_offset_y
      - .offset:         320
        .size:           8
        .value_kind:     hidden_global_offset_z
      - .offset:         328
        .size:           2
        .value_kind:     hidden_grid_dims
      - .offset:         352
        .size:           8
        .value_kind:     hidden_multigrid_sync_arg
      - .offset:         384
        .size:           4
        .value_kind:     hidden_dynamic_lds_size
    .group_segment_fixed_size: 0
    .kernarg_segment_align: 8
    .kernarg_segment_size: 520
    .language:       OpenCL C
    .language_version:
      - 2
      - 0
    .max_flat_workgroup_size: 512
    .name:           _Z4mega6Params
    .private_segment_fixed_size: 0
    .sgpr_count:     108
    .sgpr_spill_count: 83
    .symbol:         _Z4mega6Params.kd
    .uniform_work_group_size: 1
    .uses_dynamic_stack: false
    .vgpr_count:     256
    .vgpr_spill_count: 0
    .wavefront_size: 64
